# v19 + counted waits: compiler-inserted s_waitcnt vmcnt(0) at the top of the two M1 bf16 K-loops removed from steady-state iterations (kept in the peeled first iteration)
# speedup vs baseline: 1.0044x; 1.0032x over previous
; #define PG8_STAGE(bufoff, gbase, voff) do { _Pragma("unroll") for (int _i = 0; _i < 2; ++_i) \
;         __builtin_amdgcn_global_load_lds((const unsigned*)((const char*)(gbase) + (voff)[_i]), (PG8_LAS unsigned*)(lds + (bufoff) + ldsw + _i * 8192), 16, 0, 0); } while (0)
; #define PG8_LDA(dst, b, h) do { _Pragma("unroll") for (int m = 0; m < 4; ++m) _Pragma("unroll") for (int k = 0; k < 2; ++k) dst[m][k] = *(const PG8_LAS bf16x8*)(lds + PG8_SA(b, h) + aoff + m * 2048 + k * 1024); } while (0)
; #define PG8_LDB(dst, b, h) do { _Pragma("unroll") for (int n = 0; n < 2; ++n) _Pragma("unroll") for (int k = 0; k < 2; ++k) dst[n][k] = *(const PG8_LAS bf16x8*)(lds + PG8_SB(b, h) + boff + n * 2048 + k * 1024); } while (0)
; #define PG8_WAIT_V(n) asm volatile("s_waitcnt vmcnt(" #n ")" ::: "memory")
; #define PG8_WAIT_L(n) asm volatile("s_waitcnt lgkmcnt(" #n ")" ::: "memory")
; #define PG8_BAR __builtin_amdgcn_s_barrier()
; #define PG8_SCHED __builtin_amdgcn_sched_barrier(0)
;     ...
;             PG8_LDB(B0, 0, 0); PG8_LDB(B1, 0, 1); PG8_SCHED; PG8_LDA(At, 0, 0); PG8_STAGE(PG8_SA(1, 1), a1 + hstepA, voffA);
;             PG8_WAIT_V(8); PG8_WAIT_L(0); PG8_BAR; PG8_MMA(0, 0, At, B0); PG8_MMA(0, 1, At, B1); PG8_BAR; PG8_SCHED;
;             PG8_LDA(At, 0, 1); PG8_STAGE(PG8_SB(0, 0), b2, voffB); PG8_STAGE(PG8_SB(0, 1), b2 + hstepB, voffB); PG8_STAGE(PG8_SA(0, 0), a2, voffA);
;             PG8_WAIT_V(8); PG8_WAIT_L(0); PG8_BAR; PG8_MMA(1, 0, At, B0); PG8_MMA(1, 1, At, B1); PG8_BAR; PG8_SCHED;
.LBB0_923:
	v_add_u32_e32 v226, 0x10000, v153
	s_add_u32 s56, s52, 0xfff80080
	s_addc_u32 s57, s53, -1
	s_add_i32 s68, 0, 0x10000
	s_cmp_eq_u32 s47, 28
	s_cselect_b32 s59, s6, s57
	s_cselect_b32 s58, s15, s56
	s_cselect_b32 s57, s34, s41
	s_cselect_b32 s56, s35, s37
	s_add_i32 s76, 0, 0x14000
	ds_read_b128 v[132:135], v226
	ds_read_b128 v[136:139], v226 offset:1024
	ds_read_b128 v[156:159], v226 offset:2048
	ds_read_b128 v[160:163], v226 offset:3072
	ds_read_b128 v[186:189], v226 offset:16384
	ds_read_b128 v[190:193], v226 offset:17408
	ds_read_b128 v[194:197], v226 offset:18432
	ds_read_b128 v[198:201], v226 offset:19456
	s_add_i32 m0, s10, 0xc000
	ds_read_b128 v[202:205], v155
	ds_read_b128 v[206:209], v155 offset:1024
	ds_read_b128 v[210:213], v155 offset:2048
	ds_read_b128 v[214:217], v155 offset:3072
	ds_read_b128 v[218:221], v155 offset:4096
	ds_read_b128 v[222:225], v155 offset:5120
	ds_read_b128 v[234:237], v155 offset:6144
	ds_read_b128 v[238:241], v155 offset:7168
	global_load_lds_dwordx4 v148, s[52:53]
	s_add_i32 m0, s10, 0xe000
	s_nop 0
	global_load_lds_dwordx4 v150, s[52:53]
	s_waitcnt vmcnt(8)
	s_waitcnt lgkmcnt(0)
	s_barrier
	v_mfma_f32_16x16x32_bf16 v[128:131], v[132:135], v[202:205], v[128:131]
	v_mfma_f32_16x16x32_bf16 v[124:127], v[156:159], v[202:205], v[124:127]
	v_mfma_f32_16x16x32_bf16 v[112:115], v[132:135], v[210:213], v[112:115]
	v_mfma_f32_16x16x32_bf16 v[108:111], v[156:159], v[210:213], v[108:111]
	v_mfma_f32_16x16x32_bf16 v[96:99], v[132:135], v[218:221], v[96:99]
	v_mfma_f32_16x16x32_bf16 v[92:95], v[156:159], v[218:221], v[92:95]
	v_mfma_f32_16x16x32_bf16 v[80:83], v[132:135], v[234:237], v[80:83]
	v_mfma_f32_16x16x32_bf16 v[76:79], v[156:159], v[234:237], v[76:79]
	v_mfma_f32_16x16x32_bf16 v[128:131], v[136:139], v[206:209], v[128:131]
	v_mfma_f32_16x16x32_bf16 v[124:127], v[160:163], v[206:209], v[124:127]
	v_mfma_f32_16x16x32_bf16 v[112:115], v[136:139], v[214:217], v[112:115]
	v_mfma_f32_16x16x32_bf16 v[108:111], v[160:163], v[214:217], v[108:111]
	v_mfma_f32_16x16x32_bf16 v[96:99], v[136:139], v[222:225], v[96:99]
	v_mfma_f32_16x16x32_bf16 v[92:95], v[160:163], v[222:225], v[92:95]
	v_mfma_f32_16x16x32_bf16 v[80:83], v[136:139], v[238:241], v[80:83]
	v_mfma_f32_16x16x32_bf16 v[76:79], v[160:163], v[238:241], v[76:79]
	v_mfma_f32_16x16x32_bf16 v[120:123], v[186:189], v[202:205], v[120:123]
	v_mfma_f32_16x16x32_bf16 v[116:119], v[194:197], v[202:205], v[116:119]
	v_mfma_f32_16x16x32_bf16 v[104:107], v[186:189], v[210:213], v[104:107]
	v_mfma_f32_16x16x32_bf16 v[100:103], v[194:197], v[210:213], v[100:103]
	v_mfma_f32_16x16x32_bf16 v[88:91], v[186:189], v[218:221], v[88:91]
	v_mfma_f32_16x16x32_bf16 v[84:87], v[194:197], v[218:221], v[84:87]
	v_mfma_f32_16x16x32_bf16 v[72:75], v[186:189], v[234:237], v[72:75]
	v_mfma_f32_16x16x32_bf16 v[68:71], v[194:197], v[234:237], v[68:71]
	v_mfma_f32_16x16x32_bf16 v[120:123], v[190:193], v[206:209], v[120:123]
	v_mfma_f32_16x16x32_bf16 v[116:119], v[198:201], v[206:209], v[116:119]
	v_mfma_f32_16x16x32_bf16 v[104:107], v[190:193], v[214:217], v[104:107]
	v_mfma_f32_16x16x32_bf16 v[100:103], v[198:201], v[214:217], v[100:103]
	v_mfma_f32_16x16x32_bf16 v[88:91], v[190:193], v[222:225], v[88:91]
	v_mfma_f32_16x16x32_bf16 v[84:87], v[198:201], v[222:225], v[84:87]
	v_mfma_f32_16x16x32_bf16 v[72:75], v[190:193], v[238:241], v[72:75]
	v_mfma_f32_16x16x32_bf16 v[68:71], v[198:201], v[238:241], v[68:71]
	s_barrier
	s_add_i32 s68, s68, s9
	s_mov_b32 m0, s68
	ds_read_b128 v[202:205], v155 offset:16384
	ds_read_b128 v[206:209], v155 offset:17408
	ds_read_b128 v[210:213], v155 offset:18432
	ds_read_b128 v[214:217], v155 offset:19456
	ds_read_b128 v[218:221], v155 offset:20480
	ds_read_b128 v[222:225], v155 offset:21504
	ds_read_b128 v[234:237], v155 offset:22528
	ds_read_b128 v[238:241], v155 offset:23552
	global_load_lds_dwordx4 v142, s[56:57]
	s_add_i32 m0, s68, 0x2000
	s_add_u32 s70, s56, 0x80000
	s_addc_u32 s71, s57, 0
	s_add_i32 s68, s76, s9
	global_load_lds_dwordx4 v146, s[56:57]
	s_mov_b32 m0, s68
	s_add_u32 s98, s58, 0x80
	s_addc_u32 s99, s59, 0
	global_load_lds_dwordx4 v142, s[70:71]
	s_add_i32 m0, s68, 0x2000
	s_nop 0
	global_load_lds_dwordx4 v146, s[70:71]
	s_mov_b32 m0, s10
	s_nop 0
	global_load_lds_dwordx4 v140, s[58:59]
	s_mov_b32 m0, s11
	s_nop 0
	global_load_lds_dwordx4 v144, s[58:59]
	s_waitcnt vmcnt(8)
	s_waitcnt lgkmcnt(0)
	s_barrier
	v_mfma_f32_16x16x32_bf16 v[64:67], v[132:135], v[202:205], v[64:67]
	v_mfma_f32_16x16x32_bf16 v[60:63], v[156:159], v[202:205], v[60:63]
	v_mfma_f32_16x16x32_bf16 v[48:51], v[132:135], v[210:213], v[48:51]
	v_mfma_f32_16x16x32_bf16 v[44:47], v[156:159], v[210:213], v[44:47]
	v_mfma_f32_16x16x32_bf16 v[30:33], v[132:135], v[218:221], v[30:33]
	v_mfma_f32_16x16x32_bf16 v[26:29], v[156:159], v[218:221], v[26:29]
	v_mfma_f32_16x16x32_bf16 v[14:17], v[132:135], v[234:237], v[14:17]
	v_mfma_f32_16x16x32_bf16 v[10:13], v[156:159], v[234:237], v[10:13]
	v_mfma_f32_16x16x32_bf16 v[64:67], v[136:139], v[206:209], v[64:67]
	v_mfma_f32_16x16x32_bf16 v[60:63], v[160:163], v[206:209], v[60:63]
	v_mfma_f32_16x16x32_bf16 v[48:51], v[136:139], v[214:217], v[48:51]
	v_mfma_f32_16x16x32_bf16 v[44:47], v[160:163], v[214:217], v[44:47]
	v_mfma_f32_16x16x32_bf16 v[30:33], v[136:139], v[222:225], v[30:33]
	v_mfma_f32_16x16x32_bf16 v[26:29], v[160:163], v[222:225], v[26:29]
	v_mfma_f32_16x16x32_bf16 v[14:17], v[136:139], v[238:241], v[14:17]
	v_mfma_f32_16x16x32_bf16 v[10:13], v[160:163], v[238:241], v[10:13]
	v_mfma_f32_16x16x32_bf16 v[56:59], v[186:189], v[202:205], v[56:59]
	v_mfma_f32_16x16x32_bf16 v[52:55], v[194:197], v[202:205], v[52:55]
	v_mfma_f32_16x16x32_bf16 v[40:43], v[186:189], v[210:213], v[40:43]
	v_mfma_f32_16x16x32_bf16 v[36:39], v[194:197], v[210:213], v[36:39]
	v_mfma_f32_16x16x32_bf16 v[22:25], v[186:189], v[218:221], v[22:25]
	v_mfma_f32_16x16x32_bf16 v[18:21], v[194:197], v[218:221], v[18:21]
	v_mfma_f32_16x16x32_bf16 v[6:9], v[186:189], v[234:237], v[6:9]
	v_mfma_f32_16x16x32_bf16 v[2:5], v[194:197], v[234:237], v[2:5]
	v_mfma_f32_16x16x32_bf16 v[56:59], v[190:193], v[206:209], v[56:59]
	v_mfma_f32_16x16x32_bf16 v[52:55], v[198:201], v[206:209], v[52:55]
	v_mfma_f32_16x16x32_bf16 v[40:43], v[190:193], v[214:217], v[40:43]
	v_mfma_f32_16x16x32_bf16 v[36:39], v[198:201], v[214:217], v[36:39]
	v_mfma_f32_16x16x32_bf16 v[22:25], v[190:193], v[222:225], v[22:25]
	v_mfma_f32_16x16x32_bf16 v[18:21], v[198:201], v[222:225], v[18:21]
	v_mfma_f32_16x16x32_bf16 v[6:9], v[190:193], v[238:241], v[6:9]
	v_mfma_f32_16x16x32_bf16 v[2:5], v[198:201], v[238:241], v[2:5]
	s_barrier

; #define PG8_STAGE(bufoff, gbase, voff) do { _Pragma("unroll") for (int _i = 0; _i < 2; ++_i) \
;         __builtin_amdgcn_global_load_lds((const unsigned*)((const char*)(gbase) + (voff)[_i]), (PG8_LAS unsigned*)(lds + (bufoff) + ldsw + _i * 8192), 16, 0, 0); } while (0)
; #define PG8_LDA(dst, b, h) do { _Pragma("unroll") for (int m = 0; m < 4; ++m) _Pragma("unroll") for (int k = 0; k < 2; ++k) dst[m][k] = *(const PG8_LAS bf16x8*)(lds + PG8_SA(b, h) + aoff + m * 2048 + k * 1024); } while (0)
; #define PG8_LDB(dst, b, h) do { _Pragma("unroll") for (int n = 0; n < 2; ++n) _Pragma("unroll") for (int k = 0; k < 2; ++k) dst[n][k] = *(const PG8_LAS bf16x8*)(lds + PG8_SB(b, h) + boff + n * 2048 + k * 1024); } while (0)
; #define PG8_WAIT_V(n) asm volatile("s_waitcnt vmcnt(" #n ")" ::: "memory")
; #define PG8_WAIT_L(n) asm volatile("s_waitcnt lgkmcnt(" #n ")" ::: "memory")
; #define PG8_BAR __builtin_amdgcn_s_barrier()
; #define PG8_SCHED __builtin_amdgcn_sched_barrier(0)
;     ...
;             PG8_LDB(B0, 0, 0); PG8_LDB(B1, 0, 1); PG8_SCHED; PG8_LDA(At, 0, 0); PG8_STAGE(PG8_SA(1, 1), a1 + hstepA, voffA);
;             PG8_WAIT_V(8); PG8_WAIT_L(0); PG8_BAR; PG8_MMA(0, 0, At, B0); PG8_MMA(0, 1, At, B1); PG8_BAR; PG8_SCHED;
;             PG8_LDA(At, 0, 1); PG8_STAGE(PG8_SB(0, 0), b2, voffB); PG8_STAGE(PG8_SB(0, 1), b2 + hstepB, voffB); PG8_STAGE(PG8_SA(0, 0), a2, voffA);
;             PG8_WAIT_V(8); PG8_WAIT_L(0); PG8_BAR; PG8_MMA(1, 0, At, B0); PG8_MMA(1, 1, At, B1); PG8_BAR; PG8_SCHED;
.LBB0_1153:
	v_add_u32_e32 v162, 0x10000, v155
	s_add_u32 s34, s26, 0xfff80080
	s_addc_u32 s35, s27, -1
	s_add_i32 s37, 0, 0x10000
	s_cmp_eq_u32 s19, 28
	s_cselect_b32 s57, s6, s35
	s_cselect_b32 s56, s10, s34
	s_cselect_b32 s41, s11, s15
	s_cselect_b32 s40, s12, s13
	s_add_i32 s49, 0, 0x14000
	ds_read_b128 v[132:135], v162
	ds_read_b128 v[136:139], v162 offset:1024
	ds_read_b128 v[158:161], v162 offset:2048
	ds_read_b128 v[186:189], v162 offset:3072
	ds_read_b128 v[190:193], v162 offset:16384
	ds_read_b128 v[194:197], v162 offset:17408
	ds_read_b128 v[198:201], v162 offset:18432
	ds_read_b128 v[202:205], v162 offset:19456
	s_add_i32 m0, s8, 0xc000
	ds_read_b128 v[206:209], v157
	ds_read_b128 v[210:213], v157 offset:1024
	ds_read_b128 v[214:217], v157 offset:2048
	ds_read_b128 v[218:221], v157 offset:3072
	ds_read_b128 v[222:225], v157 offset:4096
	ds_read_b128 v[234:237], v157 offset:5120
	ds_read_b128 v[238:241], v157 offset:6144
	ds_read_b128 v[242:245], v157 offset:7168
	global_load_lds_dwordx4 v150, s[26:27]
	s_add_i32 m0, s8, 0xe000
	s_nop 0
	global_load_lds_dwordx4 v152, s[26:27]
	s_waitcnt vmcnt(8)
	s_waitcnt lgkmcnt(0)
	s_barrier
	v_mfma_f32_16x16x32_bf16 v[128:131], v[132:135], v[206:209], v[128:131]
	v_mfma_f32_16x16x32_bf16 v[124:127], v[158:161], v[206:209], v[124:127]
	v_mfma_f32_16x16x32_bf16 v[112:115], v[132:135], v[214:217], v[112:115]
	v_mfma_f32_16x16x32_bf16 v[108:111], v[158:161], v[214:217], v[108:111]
	v_mfma_f32_16x16x32_bf16 v[96:99], v[132:135], v[222:225], v[96:99]
	v_mfma_f32_16x16x32_bf16 v[92:95], v[158:161], v[222:225], v[92:95]
	v_mfma_f32_16x16x32_bf16 v[80:83], v[132:135], v[238:241], v[80:83]
	v_mfma_f32_16x16x32_bf16 v[76:79], v[158:161], v[238:241], v[76:79]
	v_mfma_f32_16x16x32_bf16 v[128:131], v[136:139], v[210:213], v[128:131]
	v_mfma_f32_16x16x32_bf16 v[124:127], v[186:189], v[210:213], v[124:127]
	v_mfma_f32_16x16x32_bf16 v[112:115], v[136:139], v[218:221], v[112:115]
	v_mfma_f32_16x16x32_bf16 v[108:111], v[186:189], v[218:221], v[108:111]
	v_mfma_f32_16x16x32_bf16 v[96:99], v[136:139], v[234:237], v[96:99]
	v_mfma_f32_16x16x32_bf16 v[92:95], v[186:189], v[234:237], v[92:95]
	v_mfma_f32_16x16x32_bf16 v[80:83], v[136:139], v[242:245], v[80:83]
	v_mfma_f32_16x16x32_bf16 v[76:79], v[186:189], v[242:245], v[76:79]
	v_mfma_f32_16x16x32_bf16 v[120:123], v[190:193], v[206:209], v[120:123]
	v_mfma_f32_16x16x32_bf16 v[116:119], v[198:201], v[206:209], v[116:119]
	v_mfma_f32_16x16x32_bf16 v[104:107], v[190:193], v[214:217], v[104:107]
	v_mfma_f32_16x16x32_bf16 v[100:103], v[198:201], v[214:217], v[100:103]
	v_mfma_f32_16x16x32_bf16 v[88:91], v[190:193], v[222:225], v[88:91]
	v_mfma_f32_16x16x32_bf16 v[84:87], v[198:201], v[222:225], v[84:87]
	v_mfma_f32_16x16x32_bf16 v[72:75], v[190:193], v[238:241], v[72:75]
	v_mfma_f32_16x16x32_bf16 v[68:71], v[198:201], v[238:241], v[68:71]
	v_mfma_f32_16x16x32_bf16 v[120:123], v[194:197], v[210:213], v[120:123]
	v_mfma_f32_16x16x32_bf16 v[116:119], v[202:205], v[210:213], v[116:119]
	v_mfma_f32_16x16x32_bf16 v[104:107], v[194:197], v[218:221], v[104:107]
	v_mfma_f32_16x16x32_bf16 v[100:103], v[202:205], v[218:221], v[100:103]
	v_mfma_f32_16x16x32_bf16 v[88:91], v[194:197], v[234:237], v[88:91]
	v_mfma_f32_16x16x32_bf16 v[84:87], v[202:205], v[234:237], v[84:87]
	v_mfma_f32_16x16x32_bf16 v[72:75], v[194:197], v[242:245], v[72:75]
	v_mfma_f32_16x16x32_bf16 v[68:71], v[202:205], v[242:245], v[68:71]
	s_barrier
	s_add_i32 s34, s37, s7
	s_mov_b32 m0, s34
	ds_read_b128 v[206:209], v157 offset:16384
	ds_read_b128 v[210:213], v157 offset:17408
	ds_read_b128 v[214:217], v157 offset:18432
	ds_read_b128 v[218:221], v157 offset:19456
	ds_read_b128 v[222:225], v157 offset:20480
	ds_read_b128 v[234:237], v157 offset:21504
	ds_read_b128 v[238:241], v157 offset:22528
	ds_read_b128 v[242:245], v157 offset:23552
	global_load_lds_dwordx4 v142, s[40:41]
	s_add_i32 m0, s34, 0x2000
	s_add_u32 s34, s40, 0x80000
	s_addc_u32 s35, s41, 0
	s_add_i32 s37, s49, s7
	global_load_lds_dwordx4 v146, s[40:41]
	s_mov_b32 m0, s37
	s_nop 0
	global_load_lds_dwordx4 v142, s[34:35]
	s_add_i32 m0, s37, 0x2000
	s_nop 0
	global_load_lds_dwordx4 v146, s[34:35]
	s_mov_b32 m0, s8
	s_nop 0
	global_load_lds_dwordx4 v140, s[56:57]
	s_mov_b32 m0, s9
	s_nop 0
	global_load_lds_dwordx4 v144, s[56:57]
	s_waitcnt vmcnt(8)
	s_waitcnt lgkmcnt(0)
	s_barrier
	v_mfma_f32_16x16x32_bf16 v[64:67], v[132:135], v[206:209], v[64:67]
	v_mfma_f32_16x16x32_bf16 v[60:63], v[158:161], v[206:209], v[60:63]
	v_mfma_f32_16x16x32_bf16 v[48:51], v[132:135], v[214:217], v[48:51]
	v_mfma_f32_16x16x32_bf16 v[44:47], v[158:161], v[214:217], v[44:47]
	v_mfma_f32_16x16x32_bf16 v[30:33], v[132:135], v[222:225], v[30:33]
	v_mfma_f32_16x16x32_bf16 v[26:29], v[158:161], v[222:225], v[26:29]
	v_mfma_f32_16x16x32_bf16 v[14:17], v[132:135], v[238:241], v[14:17]
	v_mfma_f32_16x16x32_bf16 v[10:13], v[158:161], v[238:241], v[10:13]
	v_mfma_f32_16x16x32_bf16 v[64:67], v[136:139], v[210:213], v[64:67]
	v_mfma_f32_16x16x32_bf16 v[60:63], v[186:189], v[210:213], v[60:63]
	v_mfma_f32_16x16x32_bf16 v[48:51], v[136:139], v[218:221], v[48:51]
	v_mfma_f32_16x16x32_bf16 v[44:47], v[186:189], v[218:221], v[44:47]
	v_mfma_f32_16x16x32_bf16 v[30:33], v[136:139], v[234:237], v[30:33]
	v_mfma_f32_16x16x32_bf16 v[26:29], v[186:189], v[234:237], v[26:29]
	v_mfma_f32_16x16x32_bf16 v[14:17], v[136:139], v[242:245], v[14:17]
	v_mfma_f32_16x16x32_bf16 v[10:13], v[186:189], v[242:245], v[10:13]
	v_mfma_f32_16x16x32_bf16 v[56:59], v[190:193], v[206:209], v[56:59]
	v_mfma_f32_16x16x32_bf16 v[52:55], v[198:201], v[206:209], v[52:55]
	v_mfma_f32_16x16x32_bf16 v[40:43], v[190:193], v[214:217], v[40:43]
	v_mfma_f32_16x16x32_bf16 v[36:39], v[198:201], v[214:217], v[36:39]
	v_mfma_f32_16x16x32_bf16 v[22:25], v[190:193], v[222:225], v[22:25]
	v_mfma_f32_16x16x32_bf16 v[18:21], v[198:201], v[222:225], v[18:21]
	v_mfma_f32_16x16x32_bf16 v[6:9], v[190:193], v[238:241], v[6:9]
	v_mfma_f32_16x16x32_bf16 v[2:5], v[198:201], v[238:241], v[2:5]
	v_mfma_f32_16x16x32_bf16 v[56:59], v[194:197], v[210:213], v[56:59]
	v_mfma_f32_16x16x32_bf16 v[52:55], v[202:205], v[210:213], v[52:55]
	v_mfma_f32_16x16x32_bf16 v[40:43], v[194:197], v[218:221], v[40:43]
	v_mfma_f32_16x16x32_bf16 v[36:39], v[202:205], v[218:221], v[36:39]
	v_mfma_f32_16x16x32_bf16 v[22:25], v[194:197], v[234:237], v[22:25]
	v_mfma_f32_16x16x32_bf16 v[18:21], v[202:205], v[234:237], v[18:21]
	v_mfma_f32_16x16x32_bf16 v[6:9], v[194:197], v[242:245], v[6:9]
	v_mfma_f32_16x16x32_bf16 v[2:5], v[202:205], v[242:245], v[2:5]
	s_barrier
